# phase 0: the partial last row of jobs (192 rope/ws jobs) moved from blocks 0-191 (which already run two modulation jobs) to blocks 256-447 (one modulation job)
# speedup vs baseline: 1.0024x; 1.0024x over previous
.LBB0_3:
	s_or_b64 exec, exec, s[6:7]
	s_load_dwordx16 s[68:83], s[0:1], 0x0
	s_load_dwordx16 s[52:67], s[0:1], 0x40
	s_cmpk_gt_i32 s2, 0x18bf
	v_and_b32_e32 v141, 63, v131
	v_lshrrev_b32_e32 v135, 6, v131
	v_lshlrev_b32_e32 v140, 2, v131
	v_lshrrev_b32_e32 v128, 4, v131
	v_lshrrev_b32_e32 v154, 2, v131
	v_lshlrev_b32_e32 v129, 4, v131
	v_lshlrev_b32_e32 v133, 3, v131
	s_cbranch_scc1 .LBB0_47
	s_mov_b32 s0, 0x979a371
	v_cvt_f64_u32_e32 v[2:3], v141
	s_mov_b32 s1, 0xbfca934f
	v_mul_f64 v[2:3], v[2:3], s[0:1]
	v_rndne_f64_e32 v[4:5], v[2:3]
	s_mov_b32 s0, 0x3b39803f
	v_add_f64 v[6:7], v[2:3], -v[4:5]
	s_mov_b32 s1, 0x3c7abc9e
	v_mul_f64 v[8:9], v[6:7], s[0:1]
	s_mov_b32 s0, 0xfefa39ef
	s_mov_b32 s1, 0x3fe62e42
	v_fmac_f64_e32 v[8:9], s[0:1], v[6:7]
	s_mov_b32 s0, 0x6a5dcb37
	v_mov_b32_e32 v6, 0xfca7ab0c
	v_mov_b32_e32 v7, 0x3e928af3
	s_mov_b32 s1, 0x3e5ade15
	v_fmac_f64_e32 v[6:7], s[0:1], v[8:9]
	v_mov_b32_e32 v10, 0x623fde64
	v_mov_b32_e32 v11, 0x3ec71dee
	v_fmac_f64_e32 v[10:11], v[8:9], v[6:7]
	v_mov_b32_e32 v6, 0x7c89e6b0
	v_mov_b32_e32 v7, 0x3efa0199
	v_fmac_f64_e32 v[6:7], v[8:9], v[10:11]
	v_mov_b32_e32 v10, 0x14761f6e
	v_mov_b32_e32 v11, 0x3f2a01a0
	v_fmac_f64_e32 v[10:11], v[8:9], v[6:7]
	v_mov_b32_e32 v6, 0x1852b7b0
	v_mov_b32_e32 v7, 0x3f56c16c
	v_fmac_f64_e32 v[6:7], v[8:9], v[10:11]
	v_mov_b32_e32 v10, 0x11122322
	v_mov_b32_e32 v11, 0x3f811111
	v_fmac_f64_e32 v[10:11], v[8:9], v[6:7]
	v_mov_b32_e32 v6, 0x555502a1
	v_mov_b32_e32 v7, 0x3fa55555
	v_fmac_f64_e32 v[6:7], v[8:9], v[10:11]
	v_mov_b32_e32 v10, 0x55555511
	v_mov_b32_e32 v11, 0x3fc55555
	s_add_u32 s6, s50, 0x1080000
	v_fmac_f64_e32 v[10:11], v[8:9], v[6:7]
	v_mov_b32_e32 v6, 11
	v_mov_b32_e32 v7, 0x3fe00000
	s_mov_b32 s0, 0
	s_addc_u32 s7, s51, 0
	v_fmac_f64_e32 v[6:7], v[8:9], v[10:11]
	s_mov_b32 s1, 0x40900000
	s_add_u32 s8, s50, 0x1200000
	v_fma_f64 v[6:7], v[8:9], v[6:7], 1.0
	v_cmp_nlt_f64_e32 vcc, s[0:1], v[2:3]
	s_mov_b32 s0, 0
	s_addc_u32 s9, s51, 0
	v_fma_f64 v[6:7], v[8:9], v[6:7], 1.0
	v_cvt_i32_f64_e32 v4, v[4:5]
	s_mov_b32 s1, 0xc090cc00
	s_add_u32 s10, s50, 0x1600000
	v_ldexp_f64 v[4:5], v[6:7], v4
	v_mov_b32_e32 v6, 0x7ff00000
	v_cmp_ngt_f64_e64 s[0:1], s[0:1], v[2:3]
	s_addc_u32 s11, s51, 0
	v_cndmask_b32_e32 v5, v6, v5, vcc
	s_and_b64 vcc, s[0:1], vcc
	s_add_u32 s12, s50, 0x10c0000
	s_addc_u32 s13, s51, 0
	s_add_u32 s30, s50, 0x1000000
	s_addc_u32 s31, s51, 0
	v_cndmask_b32_e64 v3, 0, v5, s[0:1]
	v_cndmask_b32_e32 v2, 0, v4, vcc
	s_add_u32 s14, s50, 0xc00000
	v_cvt_f32_f64_e32 v27, v[2:3]
	v_lshlrev_b32_e32 v29, 7, v135
	v_mul_u32_u24_e32 v2, 0x380, v135
	v_lshlrev_b32_e32 v3, 2, v141
	s_addc_u32 s15, s51, 0
	v_add3_u32 v30, v29, v2, v3
	v_lshlrev_b32_e32 v31, 2, v131
	v_and_b32_e32 v2, 0x3c0, v131
	s_add_u32 s16, s50, 0x2800000
	v_lshl_or_b32 v32, v2, 2, v3
	v_and_b32_e32 v2, 60, v31
	v_mov_b32_e32 v11, 0
	v_and_b32_e32 v14, 48, v129
	s_addc_u32 s17, s51, 0
	s_movk_i32 s0, 0x200
	v_lshlrev_b32_e32 v12, 2, v2
	v_and_b32_e32 v3, 0x3fc, v131
	v_mul_u32_u24_e32 v4, 0x41, v14
	s_add_u32 s18, s50, 0x1a00000
	v_mov_b32_e32 v13, v11
	s_mov_b32 s20, 0x6dc9c883
	v_or_b32_e32 v1, 0xff9f0000, v131
	v_and_b32_e32 v15, 0x7f, v131
	v_or_b32_e32 v26, 0xffaf0000, v131
	v_cmp_gt_u32_e64 s[0:1], s0, v131
	v_lshlrev_b32_e32 v28, 5, v135
	v_mul_u32_u24_e32 v33, 0x104, v128
	v_add_u32_e32 v34, 16, v128
	v_add_u32_e32 v35, 32, v128
	v_add_u32_e32 v36, 48, v128
	v_lshl_add_u32 v37, v4, 2, v3
	s_addc_u32 s19, s51, 0
	v_lshl_add_u64 v[16:17], s[46:47], 0, v[12:13]
	v_lshl_add_u64 v[18:19], s[36:37], 0, v[12:13]
	s_waitcnt lgkmcnt(0)
	v_lshl_add_u64 v[20:21], s[60:61], 0, v[12:13]
	v_lshl_add_u64 v[22:23], s[80:81], 0, v[12:13]
	v_add_u32_e32 v13, 0xffffff00, v131
	s_movk_i32 s33, 0x7fff
	s_mov_b32 s21, 0x3fc45f30
	s_movk_i32 s34, 0x3000
	s_mov_b32 s35, 0x3c000
	s_mov_b32 s36, 0x3f000
	s_mov_b32 s37, 0x42000
	s_mov_b32 s46, 0x45000
	s_mov_b32 s47, 0x48000
	v_lshlrev_b32_e32 v24, 2, v2
	s_mov_b32 s60, 0x4b000
	s_mov_b32 s61, 0x4e000
	s_mov_b32 s80, 0x51000
	s_mov_b32 s81, 0x54000
	s_mov_b32 s84, 0x57000
	s_mov_b32 s85, 0x5a000
	s_mov_b32 s86, 0x5d000
	s_mov_b32 s87, 0x7060302
	s_movk_i32 s88, 0x7000
	s_mov_b32 s89, s2
	s_mov_b32 s23, 0
	s_mov_b32 s100, 0
	s_branch .LBB0_6
.LBB0_5:
	s_add_i32 s89, s89, s3
	s_cmp_eq_u32 s3, 0x200
	s_cbranch_scc0 .Lmy_p0_lin
	s_cmpk_lt_i32 s89, 0x1800
	s_cbranch_scc1 .LBB0_6
	s_cmp_lg_u32 s100, 0
	s_cbranch_scc1 .LBB0_47
	s_mov_b32 s100, 1
	s_cmpk_lt_i32 s2, 0x100
	s_cbranch_scc1 .LBB0_47
	s_cmpk_ge_i32 s2, 0x1c0
	s_cbranch_scc1 .LBB0_47
	s_add_i32 s89, s2, 0x1700
	s_branch .LBB0_6
